# in-proj 13th column tile (gate columns only): waves with no stored column skip that unit's MFMA clusters
# speedup vs baseline: 1.0140x; 1.0036x over previous
; DEVI size_t gemm_offB(const Gemm& g, const Unit& u) { return (g.split ? (size_t)(u.b >> 2) * g.sB + (size_t)(u.b & 3) * g.sB_lo : (size_t)u.b * g.sB) + (size_t)(u.pm >> g.pmsh) * g.sBpm; }
; #define PG8_STAGE(bufoff, gbase, voff) do { _Pragma("unroll") for (int _i = 0; _i < 2; ++_i) \
;         __builtin_amdgcn_global_load_lds((const unsigned*)((const char*)(gbase) + (voff)[_i]), (LAS unsigned*)(lds + (bufoff) + ldsw + _i * 8192), 16, 0, 0); } while (0)
; #define PG8_LDA(dst, b, h) do { _Pragma("unroll") for (int m = 0; m < 4; ++m) _Pragma("unroll") for (int k = 0; k < 2; ++k) dst[m][k] = *(const LAS bf16x8*)(lds + PG8_SA(b, h) + aoff + m * 2048 + k * 1024); } while (0)
; #define PG8_LDB(dst, b, h) do { _Pragma("unroll") for (int n = 0; n < 2; ++n) _Pragma("unroll") for (int k = 0; k < 2; ++k) dst[n][k] = *(const LAS bf16x8*)(lds + PG8_SB(b, h) + boff + n * 2048 + k * 1024); } while (0)
; #define PG8_MMA(ai, bj, At, Bt) do { __builtin_amdgcn_s_setprio(1); _Pragma("unroll") for (int m = 0; m < 4; ++m) _Pragma("unroll") for (int n = 0; n < 2; ++n) _Pragma("unroll") for (int k = 0; k < 2; ++k) \
;         acc[ai][bj][m][n] = __builtin_amdgcn_mfma_f32_16x16x32_bf16(Bt[n][k], At[m][k], acc[ai][bj][m][n], 0, 0, 0); __builtin_amdgcn_s_setprio(0); } while (0)
; #define PG8_WAIT_L(n) asm volatile("s_waitcnt lgkmcnt(" #n ")" ::: "memory")
; #define PG8_BAR __builtin_amdgcn_s_barrier()
; #define PG8_SCHED __builtin_amdgcn_sched_barrier(0)
; template <class Epi>
; DEVI void gemm_phase(LAS unsigned char* lds, const Gemm g, const Epi& E) {
;     ...
;         const bool has_next = unit_next(g, ui + 1, nxt);
;         const char* nA = has_next ? (const char*)g.A + gemm_offA(g, nxt) * 2 + (size_t)nxt.pm * tstepA : cA;
;         const char* nB = has_next ? (const char*)g.Bt + gemm_offB(g, nxt) * 2 + (size_t)nxt.pn * tstepB : cB;
;         for (int t = 0; t < nt; t += 2) {
;             const bool last = (t == nt - 2);
;             const char* a1 = cA + (size_t)(t + 1) * kstep;
;             const char* a2 = last ? nA : cA + (size_t)(t + 2) * kstep; const char* b2 = last ? nB : cB + (size_t)(t + 2) * kstep;
;             const char* a3 = a2 + kstep; const char* b3 = b2 + kstep;
;             PG8_LDB(B0, 0, 0); PG8_SCHED; PG8_LDA(At, 0, 0); PG8_STAGE(PG8_SA(1, 1), a1 + hstepA, voffA);
;             PG8_WAIT_L(8); PG8_BAR; PG8_WAIT_L(0); PG8_MMA(0, 0, At, B0); PG8_BAR; PG8_SCHED;
.LBB0_275:
	s_and_b32 s101, s66, 0xc0
	s_cmp_eq_u32 s4, 12
	s_cselect_b32 s100, 1, 0
	s_cselect_b32 s101, s101, 0
	s_ashr_i32 s13, s12, 31
	v_mov_b64_e32 v[0:1], 0x680
	s_lshl_b64 s[0:1], s[12:13], 19
	v_cmp_lt_i64_e32 vcc, s[16:17], v[0:1]
	s_add_u32 s16, s24, s0
	s_addc_u32 s17, s25, s1
	s_and_b64 s[0:1], vcc, exec
	s_cselect_b32 s0, s17, s9
	s_cselect_b32 s1, s16, s8
	s_ashr_i32 s15, s14, 31
	s_lshl_b64 s[18:19], s[14:15], 19
	s_add_u32 s36, s40, s18
	s_addc_u32 s37, s41, s19
	s_and_b64 s[18:19], vcc, exec
	s_cselect_b32 s5, s37, s47
	s_cselect_b32 s7, s36, s46
	s_add_u32 s8, s8, 0x40080
	s_addc_u32 s9, s9, 0
	s_add_u32 s13, s46, 0x100
	v_mov_b32_e32 v58, 0
	s_addc_u32 s15, s47, 0
	s_mov_b32 s18, -2
	v_mov_b32_e32 v59, v58
	v_mov_b32_e32 v60, v58
	v_mov_b32_e32 v61, v58
	v_mov_b32_e32 v62, v58
	v_mov_b32_e32 v63, v58
	v_mov_b32_e32 v64, v58
	v_mov_b32_e32 v65, v58
	v_mov_b32_e32 v78, v58
	v_mov_b32_e32 v79, v58
	v_mov_b32_e32 v80, v58
	v_mov_b32_e32 v81, v58
	v_mov_b32_e32 v86, v58
	v_mov_b32_e32 v87, v58
	v_mov_b32_e32 v88, v58
	v_mov_b32_e32 v89, v58
	v_mov_b32_e32 v98, v58
	v_mov_b32_e32 v99, v58
	v_mov_b32_e32 v100, v58
	v_mov_b32_e32 v101, v58
	v_mov_b32_e32 v102, v58
	v_mov_b32_e32 v103, v58
	v_mov_b32_e32 v104, v58
	v_mov_b32_e32 v105, v58
	v_mov_b32_e32 v110, v58
	v_mov_b32_e32 v111, v58
	v_mov_b32_e32 v112, v58
	v_mov_b32_e32 v113, v58
	v_mov_b32_e32 v118, v58
	v_mov_b32_e32 v119, v58
	v_mov_b32_e32 v120, v58
	v_mov_b32_e32 v121, v58
	v_mov_b32_e32 v74, v58
	v_mov_b32_e32 v75, v58
	v_mov_b32_e32 v76, v58
	v_mov_b32_e32 v77, v58
	v_mov_b32_e32 v82, v58
	v_mov_b32_e32 v83, v58
	v_mov_b32_e32 v84, v58
	v_mov_b32_e32 v85, v58
	v_mov_b32_e32 v90, v58
	v_mov_b32_e32 v91, v58
	v_mov_b32_e32 v92, v58
	v_mov_b32_e32 v93, v58
	v_mov_b32_e32 v94, v58
	v_mov_b32_e32 v95, v58
	v_mov_b32_e32 v96, v58
	v_mov_b32_e32 v97, v58
	v_mov_b32_e32 v106, v58
	v_mov_b32_e32 v107, v58
	v_mov_b32_e32 v108, v58
	v_mov_b32_e32 v109, v58
	v_mov_b32_e32 v114, v58
	v_mov_b32_e32 v115, v58
	v_mov_b32_e32 v116, v58
	v_mov_b32_e32 v117, v58
	v_mov_b32_e32 v122, v58
	v_mov_b32_e32 v123, v58
	v_mov_b32_e32 v124, v58
	v_mov_b32_e32 v125, v58
	v_mov_b32_e32 v126, v58
	v_mov_b32_e32 v127, v58
	v_mov_b32_e32 v128, v58
	v_mov_b32_e32 v129, v58
	v_mov_b32_e32 v70, v58
	v_mov_b32_e32 v71, v58
	v_mov_b32_e32 v72, v58
	v_mov_b32_e32 v73, v58
	v_mov_b32_e32 v66, v58
	v_mov_b32_e32 v67, v58
	v_mov_b32_e32 v68, v58
	v_mov_b32_e32 v69, v58
	v_mov_b32_e32 v46, v58
	v_mov_b32_e32 v47, v58
	v_mov_b32_e32 v48, v58
	v_mov_b32_e32 v49, v58
	v_mov_b32_e32 v42, v58
	v_mov_b32_e32 v43, v58
	v_mov_b32_e32 v44, v58
	v_mov_b32_e32 v45, v58
	v_mov_b32_e32 v30, v58
	v_mov_b32_e32 v31, v58
	v_mov_b32_e32 v32, v58
	v_mov_b32_e32 v33, v58
	v_mov_b32_e32 v26, v58
	v_mov_b32_e32 v27, v58
	v_mov_b32_e32 v28, v58
	v_mov_b32_e32 v29, v58
	v_mov_b32_e32 v14, v58
	v_mov_b32_e32 v15, v58
	v_mov_b32_e32 v16, v58
	v_mov_b32_e32 v17, v58
	v_mov_b32_e32 v10, v58
	v_mov_b32_e32 v11, v58
	v_mov_b32_e32 v12, v58
	v_mov_b32_e32 v13, v58
	v_mov_b32_e32 v50, v58
	v_mov_b32_e32 v51, v58
	v_mov_b32_e32 v52, v58
	v_mov_b32_e32 v53, v58
	v_mov_b32_e32 v54, v58
	v_mov_b32_e32 v55, v58
	v_mov_b32_e32 v56, v58
	v_mov_b32_e32 v57, v58
	v_mov_b32_e32 v34, v58
	v_mov_b32_e32 v35, v58
	v_mov_b32_e32 v36, v58
	v_mov_b32_e32 v37, v58
	v_mov_b32_e32 v38, v58
	v_mov_b32_e32 v39, v58
	v_mov_b32_e32 v40, v58
	v_mov_b32_e32 v41, v58
	v_mov_b32_e32 v18, v58
	v_mov_b32_e32 v19, v58
	v_mov_b32_e32 v20, v58
	v_mov_b32_e32 v21, v58
	v_mov_b32_e32 v22, v58
	v_mov_b32_e32 v23, v58
	v_mov_b32_e32 v24, v58
	v_mov_b32_e32 v25, v58
	v_mov_b32_e32 v0, v58
	v_mov_b32_e32 v1, v58
	v_mov_b32_e32 v2, v58
	v_mov_b32_e32 v3, v58
	v_mov_b32_e32 v4, v58
	v_mov_b32_e32 v5, v58
	v_mov_b32_e32 v6, v58
	v_mov_b32_e32 v7, v58
.LBB0_276:
	s_add_u32 s19, s8, 0xfffc0080
	s_addc_u32 s26, s9, -1
	s_add_i32 s27, 0, 0x10000
	v_add_u32_e32 v8, s27, v214
	ds_read_b128 v[130:133], v8
	ds_read_b128 v[134:137], v8 offset:1024
	ds_read_b128 v[138:141], v8 offset:2048
	ds_read_b128 v[142:145], v8 offset:3072
	s_cmp_eq_u32 s18, 12
	s_cselect_b32 s69, s0, s26
	s_cselect_b32 s68, s1, s19
	s_cselect_b32 s47, s5, s15
	s_cselect_b32 s46, s7, s13
	v_lshl_add_u64 v[208:209], s[8:9], 0, v[184:185]
	s_add_i32 m0, s81, 0xc000
	ds_read_b128 v[146:149], v216
	ds_read_b128 v[150:153], v216 offset:1024
	ds_read_b128 v[188:191], v216 offset:2048
	ds_read_b128 v[192:195], v216 offset:3072
	ds_read_b128 v[196:199], v216 offset:4096
	ds_read_b128 v[200:203], v216 offset:5120
	ds_read_b128 v[204:207], v216 offset:6144
	ds_read_b128 v[218:221], v216 offset:7168
	global_load_lds_dwordx4 v[208:209], off
	v_lshl_add_u64 v[208:209], s[8:9], 0, v[186:187]
	s_add_i32 m0, s81, 0xe000
	s_nop 0
	global_load_lds_dwordx4 v[208:209], off
	s_waitcnt lgkmcnt(8)
	s_barrier
	s_waitcnt lgkmcnt(0)
	s_setprio 1
	s_waitcnt lgkmcnt(0)
	s_cmp_lg_u32 s101, 0
	s_cbranch_scc1 .Lip13_a_0
	v_mfma_f32_16x16x32_bf16 v[126:129], v[130:133], v[146:149], v[126:129]
	v_mfma_f32_16x16x32_bf16 v[122:125], v[138:141], v[146:149], v[122:125]
	v_mfma_f32_16x16x32_bf16 v[114:117], v[130:133], v[188:191], v[114:117]
	v_mfma_f32_16x16x32_bf16 v[106:109], v[138:141], v[188:191], v[106:109]
	v_mfma_f32_16x16x32_bf16 v[94:97], v[130:133], v[196:199], v[94:97]
	v_mfma_f32_16x16x32_bf16 v[90:93], v[138:141], v[196:199], v[90:93]
	v_mfma_f32_16x16x32_bf16 v[82:85], v[130:133], v[204:207], v[82:85]
	v_mfma_f32_16x16x32_bf16 v[74:77], v[138:141], v[204:207], v[74:77]
	v_mfma_f32_16x16x32_bf16 v[126:129], v[134:137], v[150:153], v[126:129]
	v_mfma_f32_16x16x32_bf16 v[122:125], v[142:145], v[150:153], v[122:125]
	v_mfma_f32_16x16x32_bf16 v[114:117], v[134:137], v[192:195], v[114:117]
	v_mfma_f32_16x16x32_bf16 v[106:109], v[142:145], v[192:195], v[106:109]
	v_mfma_f32_16x16x32_bf16 v[94:97], v[134:137], v[200:203], v[94:97]
	v_mfma_f32_16x16x32_bf16 v[90:93], v[142:145], v[200:203], v[90:93]
	v_mfma_f32_16x16x32_bf16 v[82:85], v[134:137], v[218:221], v[82:85]
	v_mfma_f32_16x16x32_bf16 v[74:77], v[142:145], v[218:221], v[74:77]
; #define PG8_STAGE(bufoff, gbase, voff) do { _Pragma("unroll") for (int _i = 0; _i < 2; ++_i) \
;         __builtin_amdgcn_global_load_lds((const unsigned*)((const char*)(gbase) + (voff)[_i]), (LAS unsigned*)(lds + (bufoff) + ldsw + _i * 8192), 16, 0, 0); } while (0)
; #define PG8_LDA(dst, b, h) do { _Pragma("unroll") for (int m = 0; m < 4; ++m) _Pragma("unroll") for (int k = 0; k < 2; ++k) dst[m][k] = *(const LAS bf16x8*)(lds + PG8_SA(b, h) + aoff + m * 2048 + k * 1024); } while (0)
; #define PG8_LDB(dst, b, h) do { _Pragma("unroll") for (int n = 0; n < 2; ++n) _Pragma("unroll") for (int k = 0; k < 2; ++k) dst[n][k] = *(const LAS bf16x8*)(lds + PG8_SB(b, h) + boff + n * 2048 + k * 1024); } while (0)
; #define PG8_MMA(ai, bj, At, Bt) do { __builtin_amdgcn_s_setprio(1); _Pragma("unroll") for (int m = 0; m < 4; ++m) _Pragma("unroll") for (int n = 0; n < 2; ++n) _Pragma("unroll") for (int k = 0; k < 2; ++k) \
;         acc[ai][bj][m][n] = __builtin_amdgcn_mfma_f32_16x16x32_bf16(Bt[n][k], At[m][k], acc[ai][bj][m][n], 0, 0, 0); __builtin_amdgcn_s_setprio(0); } while (0)
; #define PG8_WAIT_V(n) asm volatile("s_waitcnt vmcnt(" #n ")" ::: "memory")
; #define PG8_WAIT_L(n) asm volatile("s_waitcnt lgkmcnt(" #n ")" ::: "memory")
; #define PG8_BAR __builtin_amdgcn_s_barrier()
; #define PG8_SCHED __builtin_amdgcn_sched_barrier(0)
; template <class Epi>
; DEVI void gemm_phase(LAS unsigned char* lds, const Gemm g, const Epi& E) {
;     ...
;             PG8_WAIT_L(8); PG8_BAR; PG8_WAIT_L(0); PG8_MMA(0, 0, At, B0); PG8_BAR; PG8_SCHED;
;             PG8_LDB(B1, 0, 1); PG8_STAGE(PG8_SB(0, 0), b2, voffB);
;             PG8_BAR; PG8_WAIT_L(0); PG8_MMA(0, 1, At, B1); PG8_BAR;
;             PG8_LDA(At, 0, 1); PG8_STAGE(PG8_SA(0, 0), a2, voffA);
;             PG8_BAR; PG8_WAIT_L(0); PG8_MMA(1, 0, At, B0); PG8_BAR; PG8_SCHED;
;             PG8_STAGE(PG8_SB(0, 1), b2 + hstepB, voffB);
;             PG8_WAIT_V(6); PG8_BAR; PG8_MMA(1, 1, At, B1); PG8_BAR;
.Lip13_a_0:
	s_setprio 0
	s_barrier
	s_add_i32 s19, 0, 0x14000
	s_add_i32 s26, s27, s80
	v_add_u32_e32 v8, s19, v214
	v_lshl_add_u64 v[208:209], s[46:47], 0, v[178:179]
	s_mov_b32 m0, s26
	ds_read_b128 v[222:225], v8
	ds_read_b128 v[226:229], v8 offset:1024
	ds_read_b128 v[230:233], v8 offset:2048
	ds_read_b128 v[234:237], v8 offset:3072
	global_load_lds_dwordx4 v[208:209], off
	v_lshl_add_u64 v[238:239], s[46:47], 0, v[182:183]
	s_add_i32 m0, s26, 0x2000
	s_nop 0
	global_load_lds_dwordx4 v[238:239], off
	s_barrier
	s_waitcnt lgkmcnt(0)
	s_setprio 1
	s_waitcnt lgkmcnt(0)
	s_cmp_lg_u32 s100, 0
	s_cbranch_scc1 .Lip13_a_1
	v_mfma_f32_16x16x32_bf16 v[118:121], v[222:225], v[146:149], v[118:121]
	v_mfma_f32_16x16x32_bf16 v[110:113], v[230:233], v[146:149], v[110:113]
	v_mfma_f32_16x16x32_bf16 v[102:105], v[222:225], v[188:191], v[102:105]
	v_mfma_f32_16x16x32_bf16 v[98:101], v[230:233], v[188:191], v[98:101]
	v_mfma_f32_16x16x32_bf16 v[86:89], v[222:225], v[196:199], v[86:89]
	v_mfma_f32_16x16x32_bf16 v[78:81], v[230:233], v[196:199], v[78:81]
	v_mfma_f32_16x16x32_bf16 v[62:65], v[222:225], v[204:207], v[62:65]
	v_mfma_f32_16x16x32_bf16 v[58:61], v[230:233], v[204:207], v[58:61]
	v_mfma_f32_16x16x32_bf16 v[118:121], v[226:229], v[150:153], v[118:121]
	v_mfma_f32_16x16x32_bf16 v[110:113], v[234:237], v[150:153], v[110:113]
	v_mfma_f32_16x16x32_bf16 v[102:105], v[226:229], v[192:195], v[102:105]
	v_mfma_f32_16x16x32_bf16 v[98:101], v[234:237], v[192:195], v[98:101]
	v_mfma_f32_16x16x32_bf16 v[86:89], v[226:229], v[200:203], v[86:89]
	v_mfma_f32_16x16x32_bf16 v[78:81], v[234:237], v[200:203], v[78:81]
	v_mfma_f32_16x16x32_bf16 v[62:65], v[226:229], v[218:221], v[62:65]
	v_mfma_f32_16x16x32_bf16 v[58:61], v[234:237], v[218:221], v[58:61]
.Lip13_a_1:
	s_setprio 0
	s_mov_b32 m0, s81
	v_lshl_add_u64 v[240:241], s[68:69], 0, v[176:177]
	s_barrier
	ds_read_b128 v[146:149], v216 offset:16384
	ds_read_b128 v[150:153], v216 offset:17408
	ds_read_b128 v[188:191], v216 offset:18432
	ds_read_b128 v[192:195], v216 offset:19456
	ds_read_b128 v[196:199], v216 offset:20480
	ds_read_b128 v[200:203], v216 offset:21504
	ds_read_b128 v[204:207], v216 offset:22528
	ds_read_b128 v[218:221], v216 offset:23552
	global_load_lds_dwordx4 v[240:241], off
	v_lshl_add_u64 v[242:243], s[68:69], 0, v[180:181]
	s_mov_b32 m0, s82
	s_nop 0
	global_load_lds_dwordx4 v[242:243], off
	s_barrier
	s_waitcnt lgkmcnt(0)
	s_setprio 1
	s_waitcnt lgkmcnt(0)
	s_cmp_lg_u32 s101, 0
	s_cbranch_scc1 .Lip13_a_2
	v_mfma_f32_16x16x32_bf16 v[70:73], v[130:133], v[146:149], v[70:73]
	v_mfma_f32_16x16x32_bf16 v[66:69], v[138:141], v[146:149], v[66:69]
	v_mfma_f32_16x16x32_bf16 v[46:49], v[130:133], v[188:191], v[46:49]
	v_mfma_f32_16x16x32_bf16 v[42:45], v[138:141], v[188:191], v[42:45]
	v_mfma_f32_16x16x32_bf16 v[30:33], v[130:133], v[196:199], v[30:33]
	v_mfma_f32_16x16x32_bf16 v[26:29], v[138:141], v[196:199], v[26:29]
	v_mfma_f32_16x16x32_bf16 v[14:17], v[130:133], v[204:207], v[14:17]
	v_mfma_f32_16x16x32_bf16 v[10:13], v[138:141], v[204:207], v[10:13]
	v_mfma_f32_16x16x32_bf16 v[70:73], v[134:137], v[150:153], v[70:73]
	v_mfma_f32_16x16x32_bf16 v[66:69], v[142:145], v[150:153], v[66:69]
	v_mfma_f32_16x16x32_bf16 v[46:49], v[134:137], v[192:195], v[46:49]
	v_mfma_f32_16x16x32_bf16 v[42:45], v[142:145], v[192:195], v[42:45]
	v_mfma_f32_16x16x32_bf16 v[30:33], v[134:137], v[200:203], v[30:33]
	v_mfma_f32_16x16x32_bf16 v[26:29], v[142:145], v[200:203], v[26:29]
	v_mfma_f32_16x16x32_bf16 v[14:17], v[134:137], v[218:221], v[14:17]
	v_mfma_f32_16x16x32_bf16 v[10:13], v[142:145], v[218:221], v[10:13]
.Lip13_a_2:
	s_setprio 0
	s_barrier
	s_add_u32 s26, s46, 0x40000
	s_addc_u32 s27, s47, 0
	s_add_i32 s19, s19, s80
	v_lshl_add_u64 v[130:131], s[26:27], 0, v[178:179]
	s_mov_b32 m0, s19
	s_nop 0
	global_load_lds_dwordx4 v[130:131], off
	v_lshl_add_u64 v[130:131], s[26:27], 0, v[182:183]
	s_add_i32 m0, s19, 0x2000
	s_nop 0
	global_load_lds_dwordx4 v[130:131], off
	s_waitcnt vmcnt(6)
	s_barrier
	s_setprio 1
	s_cmp_lg_u32 s100, 0
	s_cbranch_scc1 .Lip13_a_3
	v_mfma_f32_16x16x32_bf16 v[50:53], v[222:225], v[146:149], v[50:53]
	v_mfma_f32_16x16x32_bf16 v[54:57], v[230:233], v[146:149], v[54:57]
	v_mfma_f32_16x16x32_bf16 v[34:37], v[222:225], v[188:191], v[34:37]
	v_mfma_f32_16x16x32_bf16 v[38:41], v[230:233], v[188:191], v[38:41]
	v_mfma_f32_16x16x32_bf16 v[18:21], v[222:225], v[196:199], v[18:21]
	v_mfma_f32_16x16x32_bf16 v[22:25], v[230:233], v[196:199], v[22:25]
	v_mfma_f32_16x16x32_bf16 v[0:3], v[222:225], v[204:207], v[0:3]
	v_mfma_f32_16x16x32_bf16 v[4:7], v[230:233], v[204:207], v[4:7]
	v_mfma_f32_16x16x32_bf16 v[50:53], v[226:229], v[150:153], v[50:53]
	v_mfma_f32_16x16x32_bf16 v[54:57], v[234:237], v[150:153], v[54:57]
	v_mfma_f32_16x16x32_bf16 v[34:37], v[226:229], v[192:195], v[34:37]
	v_mfma_f32_16x16x32_bf16 v[38:41], v[234:237], v[192:195], v[38:41]
	v_mfma_f32_16x16x32_bf16 v[18:21], v[226:229], v[200:203], v[18:21]
	v_mfma_f32_16x16x32_bf16 v[22:25], v[234:237], v[200:203], v[22:25]
	v_mfma_f32_16x16x32_bf16 v[0:3], v[226:229], v[218:221], v[0:3]
	v_mfma_f32_16x16x32_bf16 v[4:7], v[234:237], v[218:221], v[4:7]
; #define PG8_STAGE(bufoff, gbase, voff) do { _Pragma("unroll") for (int _i = 0; _i < 2; ++_i) \
;         __builtin_amdgcn_global_load_lds((const unsigned*)((const char*)(gbase) + (voff)[_i]), (LAS unsigned*)(lds + (bufoff) + ldsw + _i * 8192), 16, 0, 0); } while (0)
; #define PG8_LDA(dst, b, h) do { _Pragma("unroll") for (int m = 0; m < 4; ++m) _Pragma("unroll") for (int k = 0; k < 2; ++k) dst[m][k] = *(const LAS bf16x8*)(lds + PG8_SA(b, h) + aoff + m * 2048 + k * 1024); } while (0)
; #define PG8_LDB(dst, b, h) do { _Pragma("unroll") for (int n = 0; n < 2; ++n) _Pragma("unroll") for (int k = 0; k < 2; ++k) dst[n][k] = *(const LAS bf16x8*)(lds + PG8_SB(b, h) + boff + n * 2048 + k * 1024); } while (0)
; #define PG8_MMA(ai, bj, At, Bt) do { __builtin_amdgcn_s_setprio(1); _Pragma("unroll") for (int m = 0; m < 4; ++m) _Pragma("unroll") for (int n = 0; n < 2; ++n) _Pragma("unroll") for (int k = 0; k < 2; ++k) \
;         acc[ai][bj][m][n] = __builtin_amdgcn_mfma_f32_16x16x32_bf16(Bt[n][k], At[m][k], acc[ai][bj][m][n], 0, 0, 0); __builtin_amdgcn_s_setprio(0); } while (0)
; #define PG8_WAIT_L(n) asm volatile("s_waitcnt lgkmcnt(" #n ")" ::: "memory")
; #define PG8_BAR __builtin_amdgcn_s_barrier()
; #define PG8_SCHED __builtin_amdgcn_sched_barrier(0)
; template <class Epi>
; DEVI void gemm_phase(LAS unsigned char* lds, const Gemm g, const Epi& E) {
;     ...
;             PG8_LDB(B0, 1, 0); PG8_SCHED; PG8_LDA(At, 1, 0); PG8_STAGE(PG8_SA(0, 1), a2 + hstepA, voffA);
;             PG8_WAIT_L(8); PG8_BAR; PG8_WAIT_L(0); PG8_MMA(0, 0, At, B0); PG8_BAR; PG8_SCHED;
;             PG8_LDB(B1, 1, 1); PG8_STAGE(PG8_SB(1, 0), b3, voffB);
;             PG8_BAR; PG8_WAIT_L(0); PG8_MMA(0, 1, At, B1); PG8_BAR;
;             PG8_LDA(At, 1, 1); PG8_STAGE(PG8_SA(1, 0), a3, voffA);
;             PG8_BAR; PG8_WAIT_L(0); PG8_MMA(1, 0, At, B0); PG8_BAR; PG8_SCHED;
.Lip13_a_3:
	s_setprio 0
	s_add_i32 s19, 0, 0x18000
	v_add_u32_e32 v8, s19, v214
	s_barrier
	ds_read_b128 v[130:133], v8
	ds_read_b128 v[134:137], v8 offset:1024
	ds_read_b128 v[138:141], v8 offset:2048
	ds_read_b128 v[142:145], v8 offset:3072
	s_add_u32 s26, s68, 0x40000
	s_addc_u32 s27, s69, 0
	s_mov_b32 m0, s83
	v_lshl_add_u64 v[222:223], s[26:27], 0, v[176:177]
	ds_read_b128 v[146:149], v216 offset:32768
	ds_read_b128 v[150:153], v216 offset:33792
	ds_read_b128 v[188:191], v216 offset:34816
	ds_read_b128 v[192:195], v216 offset:35840
	ds_read_b128 v[196:199], v216 offset:36864
	ds_read_b128 v[200:203], v216 offset:37888
	ds_read_b128 v[204:207], v216 offset:38912
	ds_read_b128 v[218:221], v216 offset:39936
	global_load_lds_dwordx4 v[222:223], off
	v_lshl_add_u64 v[222:223], s[26:27], 0, v[180:181]
	s_mov_b32 m0, s84
	s_nop 0
	global_load_lds_dwordx4 v[222:223], off
	s_waitcnt lgkmcnt(8)
	s_barrier
	s_waitcnt lgkmcnt(0)
	s_setprio 1
	s_waitcnt lgkmcnt(0)
	s_cmp_lg_u32 s101, 0
	s_cbranch_scc1 .Lip13_a_4
	v_mfma_f32_16x16x32_bf16 v[126:129], v[130:133], v[146:149], v[126:129]
	v_mfma_f32_16x16x32_bf16 v[122:125], v[138:141], v[146:149], v[122:125]
	v_mfma_f32_16x16x32_bf16 v[114:117], v[130:133], v[188:191], v[114:117]
	v_mfma_f32_16x16x32_bf16 v[106:109], v[138:141], v[188:191], v[106:109]
	v_mfma_f32_16x16x32_bf16 v[94:97], v[130:133], v[196:199], v[94:97]
	v_mfma_f32_16x16x32_bf16 v[90:93], v[138:141], v[196:199], v[90:93]
	v_mfma_f32_16x16x32_bf16 v[82:85], v[130:133], v[204:207], v[82:85]
	v_mfma_f32_16x16x32_bf16 v[74:77], v[138:141], v[204:207], v[74:77]
	v_mfma_f32_16x16x32_bf16 v[126:129], v[134:137], v[150:153], v[126:129]
	v_mfma_f32_16x16x32_bf16 v[122:125], v[142:145], v[150:153], v[122:125]
	v_mfma_f32_16x16x32_bf16 v[114:117], v[134:137], v[192:195], v[114:117]
	v_mfma_f32_16x16x32_bf16 v[106:109], v[142:145], v[192:195], v[106:109]
	v_mfma_f32_16x16x32_bf16 v[94:97], v[134:137], v[200:203], v[94:97]
	v_mfma_f32_16x16x32_bf16 v[90:93], v[142:145], v[200:203], v[90:93]
	v_mfma_f32_16x16x32_bf16 v[82:85], v[134:137], v[218:221], v[82:85]
	v_mfma_f32_16x16x32_bf16 v[74:77], v[142:145], v[218:221], v[74:77]
.Lip13_a_4:
	s_setprio 0
	s_barrier
	s_add_i32 s38, 0, 0x1c000
	s_add_i32 s19, s19, s80
	v_add_u32_e32 v8, s38, v214
	v_lshl_add_u64 v[208:209], v[208:209], 0, s[70:71]
	s_mov_b32 m0, s19
	ds_read_b128 v[222:225], v8
	ds_read_b128 v[226:229], v8 offset:1024
	ds_read_b128 v[230:233], v8 offset:2048
	ds_read_b128 v[234:237], v8 offset:3072
	global_load_lds_dwordx4 v[208:209], off
	v_lshl_add_u64 v[208:209], v[238:239], 0, s[70:71]
	s_add_i32 m0, s19, 0x2000
	s_nop 0
	global_load_lds_dwordx4 v[208:209], off
	s_barrier
	s_waitcnt lgkmcnt(0)
	s_setprio 1
	s_waitcnt lgkmcnt(0)
	s_cmp_lg_u32 s100, 0
	s_cbranch_scc1 .Lip13_a_5
	v_mfma_f32_16x16x32_bf16 v[118:121], v[222:225], v[146:149], v[118:121]
	v_mfma_f32_16x16x32_bf16 v[110:113], v[230:233], v[146:149], v[110:113]
	v_mfma_f32_16x16x32_bf16 v[102:105], v[222:225], v[188:191], v[102:105]
	v_mfma_f32_16x16x32_bf16 v[98:101], v[230:233], v[188:191], v[98:101]
	v_mfma_f32_16x16x32_bf16 v[86:89], v[222:225], v[196:199], v[86:89]
	v_mfma_f32_16x16x32_bf16 v[78:81], v[230:233], v[196:199], v[78:81]
	v_mfma_f32_16x16x32_bf16 v[62:65], v[222:225], v[204:207], v[62:65]
	v_mfma_f32_16x16x32_bf16 v[58:61], v[230:233], v[204:207], v[58:61]
	v_mfma_f32_16x16x32_bf16 v[118:121], v[226:229], v[150:153], v[118:121]
	v_mfma_f32_16x16x32_bf16 v[110:113], v[234:237], v[150:153], v[110:113]
	v_mfma_f32_16x16x32_bf16 v[102:105], v[226:229], v[192:195], v[102:105]
	v_mfma_f32_16x16x32_bf16 v[98:101], v[234:237], v[192:195], v[98:101]
	v_mfma_f32_16x16x32_bf16 v[86:89], v[226:229], v[200:203], v[86:89]
	v_mfma_f32_16x16x32_bf16 v[78:81], v[234:237], v[200:203], v[78:81]
	v_mfma_f32_16x16x32_bf16 v[62:65], v[226:229], v[218:221], v[62:65]
	v_mfma_f32_16x16x32_bf16 v[58:61], v[234:237], v[218:221], v[58:61]
.Lip13_a_5:
	s_setprio 0
	s_mov_b32 m0, s85
	v_lshl_add_u64 v[208:209], v[240:241], 0, s[70:71]
	s_barrier
	ds_read_b128 v[146:149], v216 offset:49152
	ds_read_b128 v[150:153], v216 offset:50176
	ds_read_b128 v[188:191], v216 offset:51200
	ds_read_b128 v[192:195], v216 offset:52224
	ds_read_b128 v[196:199], v216 offset:53248
	ds_read_b128 v[200:203], v216 offset:54272
	ds_read_b128 v[204:207], v216 offset:55296
	ds_read_b128 v[218:221], v216 offset:56320
	global_load_lds_dwordx4 v[208:209], off
	v_lshl_add_u64 v[208:209], v[242:243], 0, s[70:71]
	s_mov_b32 m0, s86
	s_nop 0
	global_load_lds_dwordx4 v[208:209], off
	s_barrier
	s_waitcnt lgkmcnt(0)
	s_setprio 1
	s_waitcnt lgkmcnt(0)
	s_cmp_lg_u32 s101, 0
	s_cbranch_scc1 .Lip13_a_6
	v_mfma_f32_16x16x32_bf16 v[70:73], v[130:133], v[146:149], v[70:73]
	v_mfma_f32_16x16x32_bf16 v[66:69], v[138:141], v[146:149], v[66:69]
	v_mfma_f32_16x16x32_bf16 v[46:49], v[130:133], v[188:191], v[46:49]
	v_mfma_f32_16x16x32_bf16 v[42:45], v[138:141], v[188:191], v[42:45]
	v_mfma_f32_16x16x32_bf16 v[30:33], v[130:133], v[196:199], v[30:33]
	v_mfma_f32_16x16x32_bf16 v[26:29], v[138:141], v[196:199], v[26:29]
	v_mfma_f32_16x16x32_bf16 v[14:17], v[130:133], v[204:207], v[14:17]
	v_mfma_f32_16x16x32_bf16 v[10:13], v[138:141], v[204:207], v[10:13]
	v_mfma_f32_16x16x32_bf16 v[70:73], v[134:137], v[150:153], v[70:73]
	v_mfma_f32_16x16x32_bf16 v[66:69], v[142:145], v[150:153], v[66:69]
	v_mfma_f32_16x16x32_bf16 v[46:49], v[134:137], v[192:195], v[46:49]
	v_mfma_f32_16x16x32_bf16 v[42:45], v[142:145], v[192:195], v[42:45]
	v_mfma_f32_16x16x32_bf16 v[30:33], v[134:137], v[200:203], v[30:33]
	v_mfma_f32_16x16x32_bf16 v[26:29], v[142:145], v[200:203], v[26:29]
	v_mfma_f32_16x16x32_bf16 v[14:17], v[134:137], v[218:221], v[14:17]
	v_mfma_f32_16x16x32_bf16 v[10:13], v[142:145], v[218:221], v[10:13]
; #define PG8_STAGE(bufoff, gbase, voff) do { _Pragma("unroll") for (int _i = 0; _i < 2; ++_i) \
;         __builtin_amdgcn_global_load_lds((const unsigned*)((const char*)(gbase) + (voff)[_i]), (LAS unsigned*)(lds + (bufoff) + ldsw + _i * 8192), 16, 0, 0); } while (0)
; #define PG8_MMA(ai, bj, At, Bt) do { __builtin_amdgcn_s_setprio(1); _Pragma("unroll") for (int m = 0; m < 4; ++m) _Pragma("unroll") for (int n = 0; n < 2; ++n) _Pragma("unroll") for (int k = 0; k < 2; ++k) \
;         acc[ai][bj][m][n] = __builtin_amdgcn_mfma_f32_16x16x32_bf16(Bt[n][k], At[m][k], acc[ai][bj][m][n], 0, 0, 0); __builtin_amdgcn_s_setprio(0); } while (0)
; #define PG8_WAIT_V(n) asm volatile("s_waitcnt vmcnt(" #n ")" ::: "memory")
; #define PG8_BAR __builtin_amdgcn_s_barrier()
; template <class Epi>
; DEVI void gemm_phase(LAS unsigned char* lds, const Gemm g, const Epi& E) {
;     ...
;             PG8_STAGE(PG8_SB(1, 1), b3 + hstepB, voffB);
;             PG8_WAIT_V(6); PG8_BAR; PG8_MMA(1, 1, At, B1); PG8_BAR;
;         }
;         {
;             const int row0 = cur.pm * BM + wr * 64 + fr, col0 = cur.pn * BM + wc * 32 + (Epi::PERM ? 8 : 4) * fq; constexpr int NST = Epi::PERM ? 4 : 16;
;             float rsv[8];
;             if constexpr (Epi::RS) { f32x4 q4[8];
; #pragma unroll
;                 for (int i = 0; i < 8; ++i) q4[i] = *(const f32x4*)(E.ssq_in + (size_t)(row0 + (i >> 2) * HALF + (i & 3) * 16) * 4);
; #pragma unroll
;                 for (int i = 0; i < 8; ++i) rsv[i] = rsqrtf((((q4[i][0] + q4[i][1]) + q4[i][2]) + q4[i][3]) * (1.f / DM) + 1e-6f); }
.Lip13_a_6:
	s_setprio 0
	s_barrier
	s_add_u32 s26, s46, 0x40080
	s_addc_u32 s27, s47, 0
	s_add_i32 s19, s38, s80
	v_lshl_add_u64 v[130:131], s[26:27], 0, v[178:179]
	s_mov_b32 m0, s19
	s_nop 0
	global_load_lds_dwordx4 v[130:131], off
	v_lshl_add_u64 v[130:131], s[26:27], 0, v[182:183]
	s_add_i32 m0, s19, 0x2000
	s_nop 0
	global_load_lds_dwordx4 v[130:131], off
	s_waitcnt vmcnt(6)
	s_barrier
	s_setprio 1
	s_cmp_lg_u32 s100, 0
	s_cbranch_scc1 .Lip13_a_7
	v_mfma_f32_16x16x32_bf16 v[50:53], v[222:225], v[146:149], v[50:53]
	v_mfma_f32_16x16x32_bf16 v[54:57], v[230:233], v[146:149], v[54:57]
	v_mfma_f32_16x16x32_bf16 v[34:37], v[222:225], v[188:191], v[34:37]
	v_mfma_f32_16x16x32_bf16 v[38:41], v[230:233], v[188:191], v[38:41]
	v_mfma_f32_16x16x32_bf16 v[18:21], v[222:225], v[196:199], v[18:21]
	v_mfma_f32_16x16x32_bf16 v[22:25], v[230:233], v[196:199], v[22:25]
	v_mfma_f32_16x16x32_bf16 v[0:3], v[222:225], v[204:207], v[0:3]
	v_mfma_f32_16x16x32_bf16 v[4:7], v[230:233], v[204:207], v[4:7]
	v_mfma_f32_16x16x32_bf16 v[50:53], v[226:229], v[150:153], v[50:53]
	v_mfma_f32_16x16x32_bf16 v[54:57], v[234:237], v[150:153], v[54:57]
	v_mfma_f32_16x16x32_bf16 v[34:37], v[226:229], v[192:195], v[34:37]
	v_mfma_f32_16x16x32_bf16 v[38:41], v[234:237], v[192:195], v[38:41]
	v_mfma_f32_16x16x32_bf16 v[18:21], v[226:229], v[200:203], v[18:21]
	v_mfma_f32_16x16x32_bf16 v[22:25], v[234:237], v[200:203], v[22:25]
	v_mfma_f32_16x16x32_bf16 v[0:3], v[226:229], v[218:221], v[0:3]
	v_mfma_f32_16x16x32_bf16 v[4:7], v[234:237], v[218:221], v[4:7]
.Lip13_a_7:
	s_setprio 0
	s_add_i32 s18, s18, 2
	s_add_u32 s8, s8, 0x100
	s_addc_u32 s9, s9, 0
	s_add_u32 s13, s13, 0x100
	s_addc_u32 s15, s15, 0
	s_cmp_gt_u32 s18, 13
	s_barrier
	s_cbranch_scc0 .LBB0_276
	v_lshl_add_u32 v204, s6, 8, v213
	v_add_u32_e32 v188, 0xb0, v204
	v_ashrrev_i32_e32 v205, 31, v204
	v_or_b32_e32 v202, 16, v204
	v_ashrrev_i32_e32 v189, 31, v188
	v_lshl_add_u64 v[130:131], v[204:205], 4, s[76:77]
	v_ashrrev_i32_e32 v203, 31, v202
	v_lshl_add_u64 v[134:135], v[188:189], 4, s[76:77]
	global_load_dwordx4 v[206:209], v[130:131], off
	v_or_b32_e32 v200, 32, v204
	global_load_dwordx4 v[134:137], v[134:135], off
	v_lshl_add_u64 v[130:131], v[202:203], 4, s[76:77]
	global_load_dwordx4 v[218:221], v[130:131], off
	v_ashrrev_i32_e32 v201, 31, v200
	v_or_b32_e32 v198, 48, v204
	v_lshl_add_u64 v[130:131], v[200:201], 4, s[76:77]
	v_ashrrev_i32_e32 v199, 31, v198
	v_add_u32_e32 v196, 0x80, v204
	global_load_dwordx4 v[146:149], v[130:131], off
	v_lshl_add_u64 v[130:131], v[198:199], 4, s[76:77]
	v_ashrrev_i32_e32 v197, 31, v196
	v_add_u32_e32 v194, 0x90, v204
	global_load_dwordx4 v[150:153], v[130:131], off
	v_lshl_add_u64 v[130:131], v[196:197], 4, s[76:77]
	v_ashrrev_i32_e32 v195, 31, v194
	v_add_u32_e32 v192, 0xa0, v204
	global_load_dwordx4 v[138:141], v[130:131], off
	v_lshl_add_u64 v[130:131], v[194:195], 4, s[76:77]
	v_ashrrev_i32_e32 v193, 31, v192
	global_load_dwordx4 v[142:145], v[130:131], off
	v_lshl_add_u64 v[130:131], v[192:193], 4, s[76:77]
	global_load_dwordx4 v[130:133], v[130:131], off
	s_waitcnt vmcnt(0)
	v_mov_b32_e32 v191, v206
	v_mov_b32_e32 v190, v218
	v_mov_b32_e32 v206, v219
	v_pk_add_f32 v[190:191], v[190:191], v[206:207]
	v_mov_b32_e32 v206, v220
	v_mov_b32_e32 v207, v208
	v_pk_add_f32 v[190:191], v[206:207], v[190:191]
	v_mov_b32_e32 v208, v221
	v_pk_add_f32 v[190:191], v[208:209], v[190:191]
	s_nop 0
	v_pk_fma_f32 v[206:207], v[190:191], s[72:73], v[160:161] op_sel_hi:[1,0,0]
	v_lshl_or_b32 v190, s4, 8, v215
	v_mul_f32_e32 v8, 0x4b800000, v207
	v_cmp_gt_f32_e32 vcc, s94, v207
	v_cmp_gt_f32_e64 s[6:7], s94, v206
	s_nop 0
	v_cndmask_b32_e32 v8, v207, v8, vcc
	v_rsq_f32_e32 v8, v8
	s_nop 0
	v_mul_f32_e32 v162, 0x45800000, v8
	v_cndmask_b32_e32 v208, v8, v162, vcc
	v_pk_mul_f32 v[128:129], v[128:129], v[208:209] op_sel_hi:[1,0]
	v_pk_mul_f32 v[126:127], v[126:127], v[208:209] op_sel_hi:[1,0]
	v_pk_mul_f32 v[124:125], v[124:125], v[208:209] op_sel_hi:[1,0]
	v_pk_mul_f32 v[122:123], v[122:123], v[208:209] op_sel_hi:[1,0]
	v_cmp_lt_i32_e32 vcc, s39, v190
	v_add_u32_e32 v8, 0xfffff400, v190
	s_and_saveexec_b64 s[0:1], vcc
	s_xor_b64 s[8:9], exec, s[0:1]
	s_cbranch_execz .LBB0_281
	v_cmp_gt_u32_e64 s[4:5], 16, v8
	s_and_saveexec_b64 s[46:47], s[4:5]
	s_cbranch_execz .LBB0_280
	v_lshlrev_b64 v[218:219], 6, v[204:205]
	v_lshl_add_u64 v[218:219], s[58:59], 0, v[218:219]
	v_lshl_add_u64 v[218:219], v[8:9], 2, v[218:219]
	global_store_dwordx4 v[218:219], v[126:129], off
	global_store_dwordx4 v[218:219], v[122:125], off offset:16

; DEVI size_t gemm_offB(const Gemm& g, const Unit& u) { return (g.split ? (size_t)(u.b >> 2) * g.sB + (size_t)(u.b & 3) * g.sB_lo : (size_t)u.b * g.sB) + (size_t)(u.pm >> g.pmsh) * g.sBpm; }
; #define PG8_STAGE(bufoff, gbase, voff) do { _Pragma("unroll") for (int _i = 0; _i < 2; ++_i) \
;         __builtin_amdgcn_global_load_lds((const unsigned*)((const char*)(gbase) + (voff)[_i]), (LAS unsigned*)(lds + (bufoff) + ldsw + _i * 8192), 16, 0, 0); } while (0)
; #define PG8_LDA(dst, b, h) do { _Pragma("unroll") for (int m = 0; m < 4; ++m) _Pragma("unroll") for (int k = 0; k < 2; ++k) dst[m][k] = *(const LAS bf16x8*)(lds + PG8_SA(b, h) + aoff + m * 2048 + k * 1024); } while (0)
; #define PG8_LDB(dst, b, h) do { _Pragma("unroll") for (int n = 0; n < 2; ++n) _Pragma("unroll") for (int k = 0; k < 2; ++k) dst[n][k] = *(const LAS bf16x8*)(lds + PG8_SB(b, h) + boff + n * 2048 + k * 1024); } while (0)
; #define PG8_WAIT_L(n) asm volatile("s_waitcnt lgkmcnt(" #n ")" ::: "memory")
; #define PG8_BAR __builtin_amdgcn_s_barrier()
; #define PG8_SCHED __builtin_amdgcn_sched_barrier(0)
; template <class Epi>
; DEVI void gemm_phase(LAS unsigned char* lds, const Gemm g, const Epi& E) {
;     ...
;         const bool has_next = unit_next(g, ui + 1, nxt);
;         const char* nA = has_next ? (const char*)g.A + gemm_offA(g, nxt) * 2 + (size_t)nxt.pm * tstepA : cA;
;         const char* nB = has_next ? (const char*)g.Bt + gemm_offB(g, nxt) * 2 + (size_t)nxt.pn * tstepB : cB;
;         for (int t = 0; t < nt; t += 2) {
;             const bool last = (t == nt - 2);
;             const char* a1 = cA + (size_t)(t + 1) * kstep;
;             const char* a2 = last ? nA : cA + (size_t)(t + 2) * kstep; const char* b2 = last ? nB : cB + (size_t)(t + 2) * kstep;
;             const char* a3 = a2 + kstep; const char* b3 = b2 + kstep;
;             PG8_LDB(B0, 0, 0); PG8_SCHED; PG8_LDA(At, 0, 0); PG8_STAGE(PG8_SA(1, 1), a1 + hstepA, voffA);
;             PG8_WAIT_L(8); PG8_BAR; PG8_WAIT_L(0); PG8_MMA(0, 0, At, B0); PG8_BAR; PG8_SCHED;
;     ...
; #pragma unroll
;         for (int a = 0; a < 2; ++a)
; #pragma unroll
;             for (int b = 0; b < 2; ++b)
; #pragma unroll
;                 for (int m = 0; m < 4; ++m)
; #pragma unroll
;                     for (int n = 0; n < 2; ++n) acc[a][b][m][n] = (f32x4){0.f, 0.f, 0.f, 0.f};
;         cur = nxt; cA = nA; cB = nB; ++ui;
.LBB0_355:
	s_and_b32 s101, s66, 0xc0
	s_cmp_eq_u32 s4, 12
	s_cselect_b32 s100, 1, 0
	s_cselect_b32 s101, s101, 0
	s_ashr_i32 s11, s10, 31
	v_mov_b64_e32 v[0:1], 0x680
	s_lshl_b64 s[0:1], s[10:11], 19
	v_cmp_lt_i64_e32 vcc, s[14:15], v[0:1]
	s_add_u32 s14, s24, s0
	s_addc_u32 s15, s25, s1
	s_and_b64 s[0:1], vcc, exec
	s_cselect_b32 s0, s15, s9
	s_cselect_b32 s1, s14, s8
	s_ashr_i32 s13, s12, 31
	s_lshl_b64 s[16:17], s[12:13], 19
	s_add_u32 s16, s82, s16
	s_addc_u32 s17, s83, s17
	s_and_b64 s[18:19], vcc, exec
	s_cselect_b32 s5, s17, s47
	s_cselect_b32 s7, s16, s46
	s_add_u32 s8, s8, 0x40080
	s_addc_u32 s9, s9, 0
	s_add_u32 s11, s46, 0x100
	v_mov_b32_e32 v58, 0
	s_addc_u32 s13, s47, 0
	s_mov_b32 s18, -2
	v_mov_b32_e32 v59, v58
	v_mov_b32_e32 v60, v58
	v_mov_b32_e32 v61, v58
	v_mov_b32_e32 v62, v58
	v_mov_b32_e32 v63, v58
	v_mov_b32_e32 v64, v58
	v_mov_b32_e32 v65, v58
	v_mov_b32_e32 v78, v58
	v_mov_b32_e32 v79, v58
	v_mov_b32_e32 v80, v58
	v_mov_b32_e32 v81, v58
	v_mov_b32_e32 v86, v58
	v_mov_b32_e32 v87, v58
	v_mov_b32_e32 v88, v58
	v_mov_b32_e32 v89, v58
	v_mov_b32_e32 v98, v58
	v_mov_b32_e32 v99, v58
	v_mov_b32_e32 v100, v58
	v_mov_b32_e32 v101, v58
	v_mov_b32_e32 v102, v58
	v_mov_b32_e32 v103, v58
	v_mov_b32_e32 v104, v58
	v_mov_b32_e32 v105, v58
	v_mov_b32_e32 v110, v58
	v_mov_b32_e32 v111, v58
	v_mov_b32_e32 v112, v58
	v_mov_b32_e32 v113, v58
	v_mov_b32_e32 v118, v58
	v_mov_b32_e32 v119, v58
	v_mov_b32_e32 v120, v58
	v_mov_b32_e32 v121, v58
	v_mov_b32_e32 v74, v58
	v_mov_b32_e32 v75, v58
	v_mov_b32_e32 v76, v58
	v_mov_b32_e32 v77, v58
	v_mov_b32_e32 v82, v58
	v_mov_b32_e32 v83, v58
	v_mov_b32_e32 v84, v58
	v_mov_b32_e32 v85, v58
	v_mov_b32_e32 v90, v58
	v_mov_b32_e32 v91, v58
	v_mov_b32_e32 v92, v58
	v_mov_b32_e32 v93, v58
	v_mov_b32_e32 v94, v58
	v_mov_b32_e32 v95, v58
	v_mov_b32_e32 v96, v58
	v_mov_b32_e32 v97, v58
	v_mov_b32_e32 v106, v58
	v_mov_b32_e32 v107, v58
	v_mov_b32_e32 v108, v58
	v_mov_b32_e32 v109, v58
	v_mov_b32_e32 v114, v58
	v_mov_b32_e32 v115, v58
	v_mov_b32_e32 v116, v58
	v_mov_b32_e32 v117, v58
	v_mov_b32_e32 v122, v58
	v_mov_b32_e32 v123, v58
	v_mov_b32_e32 v124, v58
	v_mov_b32_e32 v125, v58
	v_mov_b32_e32 v126, v58
	v_mov_b32_e32 v127, v58
	v_mov_b32_e32 v128, v58
	v_mov_b32_e32 v129, v58
	v_mov_b32_e32 v70, v58
	v_mov_b32_e32 v71, v58
	v_mov_b32_e32 v72, v58
	v_mov_b32_e32 v73, v58
	v_mov_b32_e32 v66, v58
	v_mov_b32_e32 v67, v58
	v_mov_b32_e32 v68, v58
	v_mov_b32_e32 v69, v58
	v_mov_b32_e32 v46, v58
	v_mov_b32_e32 v47, v58
	v_mov_b32_e32 v48, v58
	v_mov_b32_e32 v49, v58
	v_mov_b32_e32 v42, v58
	v_mov_b32_e32 v43, v58
	v_mov_b32_e32 v44, v58
	v_mov_b32_e32 v45, v58
	v_mov_b32_e32 v30, v58
	v_mov_b32_e32 v31, v58
	v_mov_b32_e32 v32, v58
	v_mov_b32_e32 v33, v58
	v_mov_b32_e32 v26, v58
	v_mov_b32_e32 v27, v58
	v_mov_b32_e32 v28, v58
	v_mov_b32_e32 v29, v58
	v_mov_b32_e32 v14, v58
	v_mov_b32_e32 v15, v58
	v_mov_b32_e32 v16, v58
	v_mov_b32_e32 v17, v58
	v_mov_b32_e32 v10, v58
	v_mov_b32_e32 v11, v58
	v_mov_b32_e32 v12, v58
	v_mov_b32_e32 v13, v58
	v_mov_b32_e32 v50, v58
	v_mov_b32_e32 v51, v58
	v_mov_b32_e32 v52, v58
	v_mov_b32_e32 v53, v58
	v_mov_b32_e32 v54, v58
	v_mov_b32_e32 v55, v58
	v_mov_b32_e32 v56, v58
	v_mov_b32_e32 v57, v58
	v_mov_b32_e32 v34, v58
	v_mov_b32_e32 v35, v58
	v_mov_b32_e32 v36, v58
	v_mov_b32_e32 v37, v58
	v_mov_b32_e32 v38, v58
	v_mov_b32_e32 v39, v58
	v_mov_b32_e32 v40, v58
	v_mov_b32_e32 v41, v58
	v_mov_b32_e32 v18, v58
	v_mov_b32_e32 v19, v58
	v_mov_b32_e32 v20, v58
	v_mov_b32_e32 v21, v58
	v_mov_b32_e32 v22, v58
	v_mov_b32_e32 v23, v58
	v_mov_b32_e32 v24, v58
	v_mov_b32_e32 v25, v58
	v_mov_b32_e32 v0, v58
	v_mov_b32_e32 v1, v58
	v_mov_b32_e32 v2, v58
	v_mov_b32_e32 v3, v58
	v_mov_b32_e32 v4, v58
	v_mov_b32_e32 v5, v58
	v_mov_b32_e32 v6, v58
	v_mov_b32_e32 v7, v58
.LBB0_356:
	s_add_u32 s19, s8, 0xfffc0080
	s_addc_u32 s26, s9, -1
	s_add_i32 s27, 0, 0x10000
	v_add_u32_e32 v142, s27, v209
	ds_read_b128 v[130:133], v142
	ds_read_b128 v[134:137], v142 offset:1024
	ds_read_b128 v[138:141], v142 offset:2048
	ds_read_b128 v[142:145], v142 offset:3072
	s_cmp_eq_u32 s18, 12
	s_cselect_b32 s69, s0, s26
	s_cselect_b32 s68, s1, s19
	s_cselect_b32 s47, s5, s13
	s_cselect_b32 s46, s7, s11
	v_lshl_add_u64 v[206:207], s[8:9], 0, v[182:183]
	s_add_i32 m0, s85, 0xc000
	ds_read_b128 v[146:149], v214
	ds_read_b128 v[150:153], v214 offset:1024
	ds_read_b128 v[186:189], v214 offset:2048
	ds_read_b128 v[190:193], v214 offset:3072
	ds_read_b128 v[194:197], v214 offset:4096
	ds_read_b128 v[198:201], v214 offset:5120
	ds_read_b128 v[202:205], v214 offset:6144
	ds_read_b128 v[216:219], v214 offset:7168
	global_load_lds_dwordx4 v[206:207], off
	v_lshl_add_u64 v[206:207], s[8:9], 0, v[184:185]
	s_add_i32 m0, s85, 0xe000
	s_nop 0
	global_load_lds_dwordx4 v[206:207], off
	s_waitcnt lgkmcnt(8)
	s_barrier
	s_waitcnt lgkmcnt(0)
	s_setprio 1
	s_waitcnt lgkmcnt(0)
	s_cmp_lg_u32 s101, 0
	s_cbranch_scc1 .Lip13_b_0
	v_mfma_f32_16x16x32_bf16 v[126:129], v[130:133], v[146:149], v[126:129]
	v_mfma_f32_16x16x32_bf16 v[122:125], v[138:141], v[146:149], v[122:125]
	v_mfma_f32_16x16x32_bf16 v[114:117], v[130:133], v[186:189], v[114:117]
	v_mfma_f32_16x16x32_bf16 v[106:109], v[138:141], v[186:189], v[106:109]
	v_mfma_f32_16x16x32_bf16 v[94:97], v[130:133], v[194:197], v[94:97]
	v_mfma_f32_16x16x32_bf16 v[90:93], v[138:141], v[194:197], v[90:93]
	v_mfma_f32_16x16x32_bf16 v[82:85], v[130:133], v[202:205], v[82:85]
	v_mfma_f32_16x16x32_bf16 v[74:77], v[138:141], v[202:205], v[74:77]
	v_mfma_f32_16x16x32_bf16 v[126:129], v[134:137], v[150:153], v[126:129]
	v_mfma_f32_16x16x32_bf16 v[122:125], v[142:145], v[150:153], v[122:125]
	v_mfma_f32_16x16x32_bf16 v[114:117], v[134:137], v[190:193], v[114:117]
	v_mfma_f32_16x16x32_bf16 v[106:109], v[142:145], v[190:193], v[106:109]
	v_mfma_f32_16x16x32_bf16 v[94:97], v[134:137], v[198:201], v[94:97]
	v_mfma_f32_16x16x32_bf16 v[90:93], v[142:145], v[198:201], v[90:93]
	v_mfma_f32_16x16x32_bf16 v[82:85], v[134:137], v[216:219], v[82:85]
	v_mfma_f32_16x16x32_bf16 v[74:77], v[142:145], v[216:219], v[74:77]
; #define PG8_STAGE(bufoff, gbase, voff) do { _Pragma("unroll") for (int _i = 0; _i < 2; ++_i) \
;         __builtin_amdgcn_global_load_lds((const unsigned*)((const char*)(gbase) + (voff)[_i]), (LAS unsigned*)(lds + (bufoff) + ldsw + _i * 8192), 16, 0, 0); } while (0)
; #define PG8_LDA(dst, b, h) do { _Pragma("unroll") for (int m = 0; m < 4; ++m) _Pragma("unroll") for (int k = 0; k < 2; ++k) dst[m][k] = *(const LAS bf16x8*)(lds + PG8_SA(b, h) + aoff + m * 2048 + k * 1024); } while (0)
; #define PG8_LDB(dst, b, h) do { _Pragma("unroll") for (int n = 0; n < 2; ++n) _Pragma("unroll") for (int k = 0; k < 2; ++k) dst[n][k] = *(const LAS bf16x8*)(lds + PG8_SB(b, h) + boff + n * 2048 + k * 1024); } while (0)
; #define PG8_MMA(ai, bj, At, Bt) do { __builtin_amdgcn_s_setprio(1); _Pragma("unroll") for (int m = 0; m < 4; ++m) _Pragma("unroll") for (int n = 0; n < 2; ++n) _Pragma("unroll") for (int k = 0; k < 2; ++k) \
;         acc[ai][bj][m][n] = __builtin_amdgcn_mfma_f32_16x16x32_bf16(Bt[n][k], At[m][k], acc[ai][bj][m][n], 0, 0, 0); __builtin_amdgcn_s_setprio(0); } while (0)
; #define PG8_WAIT_V(n) asm volatile("s_waitcnt vmcnt(" #n ")" ::: "memory")
; #define PG8_WAIT_L(n) asm volatile("s_waitcnt lgkmcnt(" #n ")" ::: "memory")
; #define PG8_BAR __builtin_amdgcn_s_barrier()
; #define PG8_SCHED __builtin_amdgcn_sched_barrier(0)
; template <class Epi>
; DEVI void gemm_phase(LAS unsigned char* lds, const Gemm g, const Epi& E) {
;     ...
;             PG8_LDB(B1, 0, 1); PG8_STAGE(PG8_SB(0, 0), b2, voffB);
;             PG8_BAR; PG8_WAIT_L(0); PG8_MMA(0, 1, At, B1); PG8_BAR;
;             PG8_LDA(At, 0, 1); PG8_STAGE(PG8_SA(0, 0), a2, voffA);
;             PG8_BAR; PG8_WAIT_L(0); PG8_MMA(1, 0, At, B0); PG8_BAR; PG8_SCHED;
;             PG8_STAGE(PG8_SB(0, 1), b2 + hstepB, voffB);
;             PG8_WAIT_V(6); PG8_BAR; PG8_MMA(1, 1, At, B1); PG8_BAR;
.Lip13_b_0:
	s_setprio 0
	s_barrier
	s_add_i32 s19, 0, 0x14000
	s_add_i32 s26, s27, s84
	v_add_u32_e32 v162, s19, v209
	v_lshl_add_u64 v[206:207], s[46:47], 0, v[8:9]
	s_mov_b32 m0, s26
	ds_read_b128 v[220:223], v162
	ds_read_b128 v[224:227], v162 offset:1024
	ds_read_b128 v[228:231], v162 offset:2048
	ds_read_b128 v[232:235], v162 offset:3072
	global_load_lds_dwordx4 v[206:207], off
	v_lshl_add_u64 v[236:237], s[46:47], 0, v[180:181]
	s_add_i32 m0, s26, 0x2000
	s_nop 0
	global_load_lds_dwordx4 v[236:237], off
	s_barrier
	s_waitcnt lgkmcnt(0)
	s_setprio 1
	s_waitcnt lgkmcnt(0)
	s_cmp_lg_u32 s100, 0
	s_cbranch_scc1 .Lip13_b_1
	v_mfma_f32_16x16x32_bf16 v[118:121], v[220:223], v[146:149], v[118:121]
	v_mfma_f32_16x16x32_bf16 v[110:113], v[228:231], v[146:149], v[110:113]
	v_mfma_f32_16x16x32_bf16 v[102:105], v[220:223], v[186:189], v[102:105]
	v_mfma_f32_16x16x32_bf16 v[98:101], v[228:231], v[186:189], v[98:101]
	v_mfma_f32_16x16x32_bf16 v[86:89], v[220:223], v[194:197], v[86:89]
	v_mfma_f32_16x16x32_bf16 v[78:81], v[228:231], v[194:197], v[78:81]
	v_mfma_f32_16x16x32_bf16 v[62:65], v[220:223], v[202:205], v[62:65]
	v_mfma_f32_16x16x32_bf16 v[58:61], v[228:231], v[202:205], v[58:61]
	v_mfma_f32_16x16x32_bf16 v[118:121], v[224:227], v[150:153], v[118:121]
	v_mfma_f32_16x16x32_bf16 v[110:113], v[232:235], v[150:153], v[110:113]
	v_mfma_f32_16x16x32_bf16 v[102:105], v[224:227], v[190:193], v[102:105]
	v_mfma_f32_16x16x32_bf16 v[98:101], v[232:235], v[190:193], v[98:101]
	v_mfma_f32_16x16x32_bf16 v[86:89], v[224:227], v[198:201], v[86:89]
	v_mfma_f32_16x16x32_bf16 v[78:81], v[232:235], v[198:201], v[78:81]
	v_mfma_f32_16x16x32_bf16 v[62:65], v[224:227], v[216:219], v[62:65]
	v_mfma_f32_16x16x32_bf16 v[58:61], v[232:235], v[216:219], v[58:61]
.Lip13_b_1:
	s_setprio 0
	s_mov_b32 m0, s85
	v_lshl_add_u64 v[238:239], s[68:69], 0, v[176:177]
	s_barrier
	ds_read_b128 v[146:149], v214 offset:16384
	ds_read_b128 v[150:153], v214 offset:17408
	ds_read_b128 v[186:189], v214 offset:18432
	ds_read_b128 v[190:193], v214 offset:19456
	ds_read_b128 v[194:197], v214 offset:20480
	ds_read_b128 v[198:201], v214 offset:21504
	ds_read_b128 v[202:205], v214 offset:22528
	ds_read_b128 v[216:219], v214 offset:23552
	global_load_lds_dwordx4 v[238:239], off
	v_lshl_add_u64 v[240:241], s[68:69], 0, v[178:179]
	s_mov_b32 m0, s86
	s_nop 0
	global_load_lds_dwordx4 v[240:241], off
	s_barrier
	s_waitcnt lgkmcnt(0)
	s_setprio 1
	s_waitcnt lgkmcnt(0)
	s_cmp_lg_u32 s101, 0
	s_cbranch_scc1 .Lip13_b_2
	v_mfma_f32_16x16x32_bf16 v[70:73], v[130:133], v[146:149], v[70:73]
	v_mfma_f32_16x16x32_bf16 v[66:69], v[138:141], v[146:149], v[66:69]
	v_mfma_f32_16x16x32_bf16 v[46:49], v[130:133], v[186:189], v[46:49]
	v_mfma_f32_16x16x32_bf16 v[42:45], v[138:141], v[186:189], v[42:45]
	v_mfma_f32_16x16x32_bf16 v[30:33], v[130:133], v[194:197], v[30:33]
	v_mfma_f32_16x16x32_bf16 v[26:29], v[138:141], v[194:197], v[26:29]
	v_mfma_f32_16x16x32_bf16 v[14:17], v[130:133], v[202:205], v[14:17]
	v_mfma_f32_16x16x32_bf16 v[10:13], v[138:141], v[202:205], v[10:13]
	v_mfma_f32_16x16x32_bf16 v[70:73], v[134:137], v[150:153], v[70:73]
	v_mfma_f32_16x16x32_bf16 v[66:69], v[142:145], v[150:153], v[66:69]
	v_mfma_f32_16x16x32_bf16 v[46:49], v[134:137], v[190:193], v[46:49]
	v_mfma_f32_16x16x32_bf16 v[42:45], v[142:145], v[190:193], v[42:45]
	v_mfma_f32_16x16x32_bf16 v[30:33], v[134:137], v[198:201], v[30:33]
	v_mfma_f32_16x16x32_bf16 v[26:29], v[142:145], v[198:201], v[26:29]
	v_mfma_f32_16x16x32_bf16 v[14:17], v[134:137], v[216:219], v[14:17]
	v_mfma_f32_16x16x32_bf16 v[10:13], v[142:145], v[216:219], v[10:13]
.Lip13_b_2:
	s_setprio 0
	s_barrier
	s_add_u32 s26, s46, 0x40000
	s_addc_u32 s27, s47, 0
	s_add_i32 s19, s19, s84
	v_lshl_add_u64 v[130:131], s[26:27], 0, v[8:9]
	s_mov_b32 m0, s19
	s_nop 0
	global_load_lds_dwordx4 v[130:131], off
	v_lshl_add_u64 v[130:131], s[26:27], 0, v[180:181]
	s_add_i32 m0, s19, 0x2000
	s_nop 0
	global_load_lds_dwordx4 v[130:131], off
	s_waitcnt vmcnt(6)
	s_barrier
	s_setprio 1
	s_cmp_lg_u32 s100, 0
	s_cbranch_scc1 .Lip13_b_3
	v_mfma_f32_16x16x32_bf16 v[50:53], v[220:223], v[146:149], v[50:53]
	v_mfma_f32_16x16x32_bf16 v[54:57], v[228:231], v[146:149], v[54:57]
	v_mfma_f32_16x16x32_bf16 v[34:37], v[220:223], v[186:189], v[34:37]
	v_mfma_f32_16x16x32_bf16 v[38:41], v[228:231], v[186:189], v[38:41]
	v_mfma_f32_16x16x32_bf16 v[18:21], v[220:223], v[194:197], v[18:21]
	v_mfma_f32_16x16x32_bf16 v[22:25], v[228:231], v[194:197], v[22:25]
	v_mfma_f32_16x16x32_bf16 v[0:3], v[220:223], v[202:205], v[0:3]
	v_mfma_f32_16x16x32_bf16 v[4:7], v[228:231], v[202:205], v[4:7]
	v_mfma_f32_16x16x32_bf16 v[50:53], v[224:227], v[150:153], v[50:53]
	v_mfma_f32_16x16x32_bf16 v[54:57], v[232:235], v[150:153], v[54:57]
	v_mfma_f32_16x16x32_bf16 v[34:37], v[224:227], v[190:193], v[34:37]
	v_mfma_f32_16x16x32_bf16 v[38:41], v[232:235], v[190:193], v[38:41]
	v_mfma_f32_16x16x32_bf16 v[18:21], v[224:227], v[198:201], v[18:21]
	v_mfma_f32_16x16x32_bf16 v[22:25], v[232:235], v[198:201], v[22:25]
	v_mfma_f32_16x16x32_bf16 v[0:3], v[224:227], v[216:219], v[0:3]
	v_mfma_f32_16x16x32_bf16 v[4:7], v[232:235], v[216:219], v[4:7]
; #define PG8_STAGE(bufoff, gbase, voff) do { _Pragma("unroll") for (int _i = 0; _i < 2; ++_i) \
;         __builtin_amdgcn_global_load_lds((const unsigned*)((const char*)(gbase) + (voff)[_i]), (LAS unsigned*)(lds + (bufoff) + ldsw + _i * 8192), 16, 0, 0); } while (0)
; #define PG8_LDA(dst, b, h) do { _Pragma("unroll") for (int m = 0; m < 4; ++m) _Pragma("unroll") for (int k = 0; k < 2; ++k) dst[m][k] = *(const LAS bf16x8*)(lds + PG8_SA(b, h) + aoff + m * 2048 + k * 1024); } while (0)
; #define PG8_LDB(dst, b, h) do { _Pragma("unroll") for (int n = 0; n < 2; ++n) _Pragma("unroll") for (int k = 0; k < 2; ++k) dst[n][k] = *(const LAS bf16x8*)(lds + PG8_SB(b, h) + boff + n * 2048 + k * 1024); } while (0)
; #define PG8_MMA(ai, bj, At, Bt) do { __builtin_amdgcn_s_setprio(1); _Pragma("unroll") for (int m = 0; m < 4; ++m) _Pragma("unroll") for (int n = 0; n < 2; ++n) _Pragma("unroll") for (int k = 0; k < 2; ++k) \
;         acc[ai][bj][m][n] = __builtin_amdgcn_mfma_f32_16x16x32_bf16(Bt[n][k], At[m][k], acc[ai][bj][m][n], 0, 0, 0); __builtin_amdgcn_s_setprio(0); } while (0)
; #define PG8_WAIT_L(n) asm volatile("s_waitcnt lgkmcnt(" #n ")" ::: "memory")
; #define PG8_BAR __builtin_amdgcn_s_barrier()
; #define PG8_SCHED __builtin_amdgcn_sched_barrier(0)
; template <class Epi>
; DEVI void gemm_phase(LAS unsigned char* lds, const Gemm g, const Epi& E) {
;     ...
;             PG8_LDB(B0, 1, 0); PG8_SCHED; PG8_LDA(At, 1, 0); PG8_STAGE(PG8_SA(0, 1), a2 + hstepA, voffA);
;             PG8_WAIT_L(8); PG8_BAR; PG8_WAIT_L(0); PG8_MMA(0, 0, At, B0); PG8_BAR; PG8_SCHED;
;             PG8_LDB(B1, 1, 1); PG8_STAGE(PG8_SB(1, 0), b3, voffB);
;             PG8_BAR; PG8_WAIT_L(0); PG8_MMA(0, 1, At, B1); PG8_BAR;
;             PG8_LDA(At, 1, 1); PG8_STAGE(PG8_SA(1, 0), a3, voffA);
;             PG8_BAR; PG8_WAIT_L(0); PG8_MMA(1, 0, At, B0); PG8_BAR; PG8_SCHED;
.Lip13_b_3:
	s_setprio 0
	s_add_i32 s19, 0, 0x18000
	v_add_u32_e32 v142, s19, v209
	s_barrier
	ds_read_b128 v[130:133], v142
	ds_read_b128 v[134:137], v142 offset:1024
	ds_read_b128 v[138:141], v142 offset:2048
	ds_read_b128 v[142:145], v142 offset:3072
	s_add_u32 s26, s68, 0x40000
	s_addc_u32 s27, s69, 0
	s_mov_b32 m0, s87
	v_lshl_add_u64 v[220:221], s[26:27], 0, v[176:177]
	ds_read_b128 v[146:149], v214 offset:32768
	ds_read_b128 v[150:153], v214 offset:33792
	ds_read_b128 v[186:189], v214 offset:34816
	ds_read_b128 v[190:193], v214 offset:35840
	ds_read_b128 v[194:197], v214 offset:36864
	ds_read_b128 v[198:201], v214 offset:37888
	ds_read_b128 v[202:205], v214 offset:38912
	ds_read_b128 v[216:219], v214 offset:39936
	global_load_lds_dwordx4 v[220:221], off
	v_lshl_add_u64 v[220:221], s[26:27], 0, v[178:179]
	s_mov_b32 m0, s88
	s_nop 0
	global_load_lds_dwordx4 v[220:221], off
	s_waitcnt lgkmcnt(8)
	s_barrier
	s_waitcnt lgkmcnt(0)
	s_setprio 1
	s_waitcnt lgkmcnt(0)
	s_cmp_lg_u32 s101, 0
	s_cbranch_scc1 .Lip13_b_4
	v_mfma_f32_16x16x32_bf16 v[126:129], v[130:133], v[146:149], v[126:129]
	v_mfma_f32_16x16x32_bf16 v[122:125], v[138:141], v[146:149], v[122:125]
	v_mfma_f32_16x16x32_bf16 v[114:117], v[130:133], v[186:189], v[114:117]
	v_mfma_f32_16x16x32_bf16 v[106:109], v[138:141], v[186:189], v[106:109]
	v_mfma_f32_16x16x32_bf16 v[94:97], v[130:133], v[194:197], v[94:97]
	v_mfma_f32_16x16x32_bf16 v[90:93], v[138:141], v[194:197], v[90:93]
	v_mfma_f32_16x16x32_bf16 v[82:85], v[130:133], v[202:205], v[82:85]
	v_mfma_f32_16x16x32_bf16 v[74:77], v[138:141], v[202:205], v[74:77]
	v_mfma_f32_16x16x32_bf16 v[126:129], v[134:137], v[150:153], v[126:129]
	v_mfma_f32_16x16x32_bf16 v[122:125], v[142:145], v[150:153], v[122:125]
	v_mfma_f32_16x16x32_bf16 v[114:117], v[134:137], v[190:193], v[114:117]
	v_mfma_f32_16x16x32_bf16 v[106:109], v[142:145], v[190:193], v[106:109]
	v_mfma_f32_16x16x32_bf16 v[94:97], v[134:137], v[198:201], v[94:97]
	v_mfma_f32_16x16x32_bf16 v[90:93], v[142:145], v[198:201], v[90:93]
	v_mfma_f32_16x16x32_bf16 v[82:85], v[134:137], v[216:219], v[82:85]
	v_mfma_f32_16x16x32_bf16 v[74:77], v[142:145], v[216:219], v[74:77]
.Lip13_b_4:
	s_setprio 0
	s_barrier
	s_add_i32 s38, 0, 0x1c000
	s_add_i32 s19, s19, s84
	v_add_u32_e32 v162, s38, v209
	v_lshl_add_u64 v[206:207], v[206:207], 0, s[70:71]
	s_mov_b32 m0, s19
	ds_read_b128 v[220:223], v162
	ds_read_b128 v[224:227], v162 offset:1024
	ds_read_b128 v[228:231], v162 offset:2048
	ds_read_b128 v[232:235], v162 offset:3072
	global_load_lds_dwordx4 v[206:207], off
	v_lshl_add_u64 v[206:207], v[236:237], 0, s[70:71]
	s_add_i32 m0, s19, 0x2000
	s_nop 0
	global_load_lds_dwordx4 v[206:207], off
	s_barrier
	s_waitcnt lgkmcnt(0)
	s_setprio 1
	s_waitcnt lgkmcnt(0)
	s_cmp_lg_u32 s100, 0
	s_cbranch_scc1 .Lip13_b_5
	v_mfma_f32_16x16x32_bf16 v[118:121], v[220:223], v[146:149], v[118:121]
	v_mfma_f32_16x16x32_bf16 v[110:113], v[228:231], v[146:149], v[110:113]
	v_mfma_f32_16x16x32_bf16 v[102:105], v[220:223], v[186:189], v[102:105]
	v_mfma_f32_16x16x32_bf16 v[98:101], v[228:231], v[186:189], v[98:101]
	v_mfma_f32_16x16x32_bf16 v[86:89], v[220:223], v[194:197], v[86:89]
	v_mfma_f32_16x16x32_bf16 v[78:81], v[228:231], v[194:197], v[78:81]
	v_mfma_f32_16x16x32_bf16 v[62:65], v[220:223], v[202:205], v[62:65]
	v_mfma_f32_16x16x32_bf16 v[58:61], v[228:231], v[202:205], v[58:61]
	v_mfma_f32_16x16x32_bf16 v[118:121], v[224:227], v[150:153], v[118:121]
	v_mfma_f32_16x16x32_bf16 v[110:113], v[232:235], v[150:153], v[110:113]
	v_mfma_f32_16x16x32_bf16 v[102:105], v[224:227], v[190:193], v[102:105]
	v_mfma_f32_16x16x32_bf16 v[98:101], v[232:235], v[190:193], v[98:101]
	v_mfma_f32_16x16x32_bf16 v[86:89], v[224:227], v[198:201], v[86:89]
	v_mfma_f32_16x16x32_bf16 v[78:81], v[232:235], v[198:201], v[78:81]
	v_mfma_f32_16x16x32_bf16 v[62:65], v[224:227], v[216:219], v[62:65]
	v_mfma_f32_16x16x32_bf16 v[58:61], v[232:235], v[216:219], v[58:61]
.Lip13_b_5:
	s_setprio 0
	s_mov_b32 m0, s89
	v_lshl_add_u64 v[206:207], v[238:239], 0, s[70:71]
	s_barrier
	ds_read_b128 v[146:149], v214 offset:49152
	ds_read_b128 v[150:153], v214 offset:50176
	ds_read_b128 v[186:189], v214 offset:51200
	ds_read_b128 v[190:193], v214 offset:52224
	ds_read_b128 v[194:197], v214 offset:53248
	ds_read_b128 v[198:201], v214 offset:54272
	ds_read_b128 v[202:205], v214 offset:55296
	ds_read_b128 v[216:219], v214 offset:56320
	global_load_lds_dwordx4 v[206:207], off
	v_lshl_add_u64 v[206:207], v[240:241], 0, s[70:71]
	s_mov_b32 m0, s90
	s_nop 0
	global_load_lds_dwordx4 v[206:207], off
	s_barrier
	s_waitcnt lgkmcnt(0)
	s_setprio 1
	s_waitcnt lgkmcnt(0)
	s_cmp_lg_u32 s101, 0
	s_cbranch_scc1 .Lip13_b_6
	v_mfma_f32_16x16x32_bf16 v[70:73], v[130:133], v[146:149], v[70:73]
	v_mfma_f32_16x16x32_bf16 v[66:69], v[138:141], v[146:149], v[66:69]
	v_mfma_f32_16x16x32_bf16 v[46:49], v[130:133], v[186:189], v[46:49]
	v_mfma_f32_16x16x32_bf16 v[42:45], v[138:141], v[186:189], v[42:45]
	v_mfma_f32_16x16x32_bf16 v[30:33], v[130:133], v[194:197], v[30:33]
	v_mfma_f32_16x16x32_bf16 v[26:29], v[138:141], v[194:197], v[26:29]
	v_mfma_f32_16x16x32_bf16 v[14:17], v[130:133], v[202:205], v[14:17]
	v_mfma_f32_16x16x32_bf16 v[10:13], v[138:141], v[202:205], v[10:13]
	v_mfma_f32_16x16x32_bf16 v[70:73], v[134:137], v[150:153], v[70:73]
	v_mfma_f32_16x16x32_bf16 v[66:69], v[142:145], v[150:153], v[66:69]
	v_mfma_f32_16x16x32_bf16 v[46:49], v[134:137], v[190:193], v[46:49]
	v_mfma_f32_16x16x32_bf16 v[42:45], v[142:145], v[190:193], v[42:45]
	v_mfma_f32_16x16x32_bf16 v[30:33], v[134:137], v[198:201], v[30:33]
	v_mfma_f32_16x16x32_bf16 v[26:29], v[142:145], v[198:201], v[26:29]
	v_mfma_f32_16x16x32_bf16 v[14:17], v[134:137], v[216:219], v[14:17]
	v_mfma_f32_16x16x32_bf16 v[10:13], v[142:145], v[216:219], v[10:13]
; #define PG8_STAGE(bufoff, gbase, voff) do { _Pragma("unroll") for (int _i = 0; _i < 2; ++_i) \
;         __builtin_amdgcn_global_load_lds((const unsigned*)((const char*)(gbase) + (voff)[_i]), (LAS unsigned*)(lds + (bufoff) + ldsw + _i * 8192), 16, 0, 0); } while (0)
; #define PG8_MMA(ai, bj, At, Bt) do { __builtin_amdgcn_s_setprio(1); _Pragma("unroll") for (int m = 0; m < 4; ++m) _Pragma("unroll") for (int n = 0; n < 2; ++n) _Pragma("unroll") for (int k = 0; k < 2; ++k) \
;         acc[ai][bj][m][n] = __builtin_amdgcn_mfma_f32_16x16x32_bf16(Bt[n][k], At[m][k], acc[ai][bj][m][n], 0, 0, 0); __builtin_amdgcn_s_setprio(0); } while (0)
; #define PG8_WAIT_V(n) asm volatile("s_waitcnt vmcnt(" #n ")" ::: "memory")
; #define PG8_BAR __builtin_amdgcn_s_barrier()
; template <class Epi>
; DEVI void gemm_phase(LAS unsigned char* lds, const Gemm g, const Epi& E) {
;     ...
;             PG8_STAGE(PG8_SB(1, 1), b3 + hstepB, voffB);
;             PG8_WAIT_V(6); PG8_BAR; PG8_MMA(1, 1, At, B1); PG8_BAR;
;         }
;         {
;             const int row0 = cur.pm * BM + wr * 64 + fr, col0 = cur.pn * BM + wc * 32 + (Epi::PERM ? 8 : 4) * fq; constexpr int NST = Epi::PERM ? 4 : 16;
;             float rsv[8];
;             if constexpr (Epi::RS) { f32x4 q4[8];
; #pragma unroll
;                 for (int i = 0; i < 8; ++i) q4[i] = *(const f32x4*)(E.ssq_in + (size_t)(row0 + (i >> 2) * HALF + (i & 3) * 16) * 4);
; #pragma unroll
;                 for (int i = 0; i < 8; ++i) rsv[i] = rsqrtf((((q4[i][0] + q4[i][1]) + q4[i][2]) + q4[i][3]) * (1.f / DM) + 1e-6f); }
.Lip13_b_6:
	s_setprio 0
	s_barrier
	s_add_u32 s26, s46, 0x40080
	s_addc_u32 s27, s47, 0
	s_add_i32 s19, s38, s84
	v_lshl_add_u64 v[130:131], s[26:27], 0, v[8:9]
	s_mov_b32 m0, s19
	s_nop 0
	global_load_lds_dwordx4 v[130:131], off
	v_lshl_add_u64 v[130:131], s[26:27], 0, v[180:181]
	s_add_i32 m0, s19, 0x2000
	s_nop 0
	global_load_lds_dwordx4 v[130:131], off
	s_waitcnt vmcnt(6)
	s_barrier
	s_setprio 1
	s_cmp_lg_u32 s100, 0
	s_cbranch_scc1 .Lip13_b_7
	v_mfma_f32_16x16x32_bf16 v[50:53], v[220:223], v[146:149], v[50:53]
	v_mfma_f32_16x16x32_bf16 v[54:57], v[228:231], v[146:149], v[54:57]
	v_mfma_f32_16x16x32_bf16 v[34:37], v[220:223], v[186:189], v[34:37]
	v_mfma_f32_16x16x32_bf16 v[38:41], v[228:231], v[186:189], v[38:41]
	v_mfma_f32_16x16x32_bf16 v[18:21], v[220:223], v[194:197], v[18:21]
	v_mfma_f32_16x16x32_bf16 v[22:25], v[228:231], v[194:197], v[22:25]
	v_mfma_f32_16x16x32_bf16 v[0:3], v[220:223], v[202:205], v[0:3]
	v_mfma_f32_16x16x32_bf16 v[4:7], v[228:231], v[202:205], v[4:7]
	v_mfma_f32_16x16x32_bf16 v[50:53], v[224:227], v[150:153], v[50:53]
	v_mfma_f32_16x16x32_bf16 v[54:57], v[232:235], v[150:153], v[54:57]
	v_mfma_f32_16x16x32_bf16 v[34:37], v[224:227], v[190:193], v[34:37]
	v_mfma_f32_16x16x32_bf16 v[38:41], v[232:235], v[190:193], v[38:41]
	v_mfma_f32_16x16x32_bf16 v[18:21], v[224:227], v[198:201], v[18:21]
	v_mfma_f32_16x16x32_bf16 v[22:25], v[232:235], v[198:201], v[22:25]
	v_mfma_f32_16x16x32_bf16 v[0:3], v[224:227], v[216:219], v[0:3]
	v_mfma_f32_16x16x32_bf16 v[4:7], v[232:235], v[216:219], v[4:7]
.Lip13_b_7:
	s_setprio 0
	s_add_i32 s18, s18, 2
	s_add_u32 s8, s8, 0x100
	s_addc_u32 s9, s9, 0
	s_add_u32 s11, s11, 0x100
	s_addc_u32 s13, s13, 0
	s_cmp_gt_u32 s18, 13
	s_barrier
	s_cbranch_scc0 .LBB0_356
	v_lshl_add_u32 v202, s6, 8, v208
	v_ashrrev_i32_e32 v203, 31, v202
	v_or_b32_e32 v200, 16, v202
	v_lshl_add_u64 v[130:131], v[202:203], 4, s[76:77]
	v_ashrrev_i32_e32 v201, 31, v200
	v_lshl_add_u64 v[132:133], v[200:201], 4, s[76:77]
	global_load_dwordx4 v[204:207], v[130:131], off
	global_load_dwordx4 v[216:219], v[132:133], off
	v_or_b32_e32 v198, 32, v202
	v_ashrrev_i32_e32 v199, 31, v198
	v_or_b32_e32 v196, 48, v202
	v_add_u32_e32 v194, 0x80, v202
	v_lshl_add_u64 v[130:131], v[198:199], 4, s[76:77]
	v_ashrrev_i32_e32 v197, 31, v196
	v_ashrrev_i32_e32 v195, 31, v194
	v_add_u32_e32 v192, 0x90, v202
	v_add_u32_e32 v190, 0xa0, v202
	v_add_u32_e32 v188, 0xb0, v202
	v_lshl_add_u64 v[132:133], v[196:197], 4, s[76:77]
	global_load_dwordx4 v[146:149], v[130:131], off
	global_load_dwordx4 v[150:153], v[132:133], off
	v_lshl_add_u64 v[130:131], v[194:195], 4, s[76:77]
	v_ashrrev_i32_e32 v193, 31, v192
	v_ashrrev_i32_e32 v191, 31, v190
	v_ashrrev_i32_e32 v189, 31, v188
	v_lshl_add_u64 v[132:133], v[192:193], 4, s[76:77]
	global_load_dwordx4 v[138:141], v[130:131], off
	global_load_dwordx4 v[142:145], v[132:133], off
	v_lshl_add_u64 v[130:131], v[190:191], 4, s[76:77]
	v_lshl_add_u64 v[134:135], v[188:189], 4, s[76:77]
	global_load_dwordx4 v[130:133], v[130:131], off
	s_nop 0
	global_load_dwordx4 v[134:137], v[134:135], off
	s_waitcnt vmcnt(0)
	v_mov_b32_e32 v187, v204
	v_mov_b32_e32 v186, v216
	v_mov_b32_e32 v204, v217
	v_mov_b32_e32 v221, v206
	v_mov_b32_e32 v220, v218
	v_pk_add_f32 v[186:187], v[186:187], v[204:205]
	v_mov_b32_e32 v206, v219
	v_pk_add_f32 v[186:187], v[220:221], v[186:187]
	s_nop 0
	v_pk_add_f32 v[186:187], v[206:207], v[186:187]
	s_nop 0
	v_pk_fma_f32 v[204:205], v[186:187], s[72:73], v[160:161] op_sel_hi:[1,0,0]
	v_lshl_or_b32 v186, s4, 8, v213
	v_mul_f32_e32 v162, 0x4b800000, v205
	v_cmp_gt_f32_e32 vcc, s94, v205
	v_cmp_gt_f32_e64 s[6:7], s94, v204
	s_nop 0
	v_cndmask_b32_e32 v162, v205, v162, vcc
	v_rsq_f32_e32 v162, v162
	s_nop 0
	v_mul_f32_e32 v163, 0x45800000, v162
	v_cndmask_b32_e32 v206, v162, v163, vcc
	v_pk_mul_f32 v[128:129], v[128:129], v[206:207] op_sel_hi:[1,0]
	v_pk_mul_f32 v[126:127], v[126:127], v[206:207] op_sel_hi:[1,0]
	v_pk_mul_f32 v[124:125], v[124:125], v[206:207] op_sel_hi:[1,0]
	v_pk_mul_f32 v[122:123], v[122:123], v[206:207] op_sel_hi:[1,0]
	v_cmp_lt_i32_e32 vcc, s52, v186
	s_and_saveexec_b64 s[0:1], vcc
	s_xor_b64 s[8:9], exec, s[0:1]
	s_cbranch_execz .LBB0_361
	v_cmp_eq_u32_e64 s[4:5], s53, v186
	s_and_saveexec_b64 s[46:47], s[4:5]
	s_cbranch_execz .LBB0_360
	v_lshlrev_b64 v[216:217], 6, v[202:203]
	v_lshl_add_u64 v[216:217], s[58:59], 0, v[216:217]
	global_store_dwordx4 v[216:217], v[126:129], off
	global_store_dwordx4 v[216:217], v[122:125], off offset:16
